# same as previous version but without the nt hint on SCAN's scattered 4-byte final-state stores (partial-line writes should merge in L2)
# baseline (speedup 1.0000x reference)
.LBB0_1155:
	s_waitcnt vmcnt(0)
	v_ashrrev_i32_e32 v2, 13, v4
	v_bfe_u32 v10, v4, 5, 8
	v_and_b32_e32 v9, 0x7c, v5
	v_and_b32_e32 v0, 7, v2
	v_lshl_or_b32 v11, v10, 7, v9
	v_lshlrev_b32_e32 v14, 5, v2
	v_cvt_f32_ubyte0_e32 v17, v0
	v_lshlrev_b32_e32 v0, 2, v11
	v_ashrrev_i32_e32 v15, 31, v14
	v_or_b32_e32 v16, 1, v14
	v_lshl_add_u64 v[78:79], s[4:5], 0, v[0:1]
	v_lshlrev_b64 v[80:81], 17, v[14:15]
	v_or_b32_e32 v18, 2, v14
	v_or_b32_e32 v20, 3, v14
	v_or_b32_e32 v22, 4, v14
	v_or_b32_e32 v24, 5, v14
	v_or_b32_e32 v26, 6, v14
	v_or_b32_e32 v28, 7, v14
	v_or_b32_e32 v30, 8, v14
	v_or_b32_e32 v32, 9, v14
	v_or_b32_e32 v34, 10, v14
	v_or_b32_e32 v36, 11, v14
	v_or_b32_e32 v38, 12, v14
	v_or_b32_e32 v40, 13, v14
	v_or_b32_e32 v42, 14, v14
	v_or_b32_e32 v44, 15, v14
	v_or_b32_e32 v46, 16, v14
	v_or_b32_e32 v48, 17, v14
	v_or_b32_e32 v50, 18, v14
	v_or_b32_e32 v52, 19, v14
	v_or_b32_e32 v54, 20, v14
	v_or_b32_e32 v56, 21, v14
	v_or_b32_e32 v58, 22, v14
	v_or_b32_e32 v60, 23, v14
	v_or_b32_e32 v62, 24, v14
	v_or_b32_e32 v64, 25, v14
	v_or_b32_e32 v66, 26, v14
	v_or_b32_e32 v68, 27, v14
	v_or_b32_e32 v70, 28, v14
	v_or_b32_e32 v72, 29, v14
	v_or_b32_e32 v74, 30, v14
	v_or_b32_e32 v76, 31, v14
	v_sub_f32_e32 v129, 0xc0a00000, v17
	v_ashrrev_i32_e32 v17, 31, v16
	v_lshlrev_b64 v[82:83], 16, v[14:15]
	v_lshl_add_u64 v[14:15], v[78:79], 0, v[80:81]
	v_lshlrev_b64 v[80:81], 17, v[16:17]
	v_lshlrev_b64 v[148:149], 16, v[16:17]
	global_load_dwordx4 v[14:17], v[14:15], off nt
	v_add_u32_e32 v4, s12, v4
	v_cmp_lt_i32_e32 vcc, s16, v4
	s_or_b64 s[10:11], vcc, s[10:11]
	v_cmp_gt_f32_e32 vcc, s14, v129
	v_ashrrev_i32_e32 v19, 31, v18
	v_ashrrev_i32_e32 v21, 31, v20
	v_ashrrev_i32_e32 v23, 31, v22
	v_ashrrev_i32_e32 v25, 31, v24
	v_ashrrev_i32_e32 v27, 31, v26
	v_ashrrev_i32_e32 v29, 31, v28
	v_ashrrev_i32_e32 v31, 31, v30
	v_ashrrev_i32_e32 v33, 31, v32
	v_ashrrev_i32_e32 v35, 31, v34
	v_ashrrev_i32_e32 v37, 31, v36
	v_ashrrev_i32_e32 v39, 31, v38
	v_ashrrev_i32_e32 v41, 31, v40
	v_lshlrev_b32_e32 v0, 1, v11
	v_cndmask_b32_e32 v11, 0, v6, vcc
	v_lshlrev_b64 v[84:85], 17, v[18:19]
	v_lshlrev_b64 v[86:87], 17, v[20:21]
	v_lshlrev_b64 v[88:89], 17, v[22:23]
	v_lshlrev_b64 v[90:91], 17, v[24:25]
	v_lshlrev_b64 v[92:93], 17, v[26:27]
	v_lshlrev_b64 v[94:95], 17, v[28:29]
	v_lshlrev_b64 v[96:97], 17, v[30:31]
	v_lshlrev_b64 v[98:99], 17, v[32:33]
	v_lshlrev_b64 v[100:101], 17, v[34:35]
	v_lshlrev_b64 v[102:103], 17, v[36:37]
	v_lshlrev_b64 v[104:105], 17, v[38:39]
	v_lshlrev_b64 v[106:107], 17, v[40:41]
	v_lshl_add_u64 v[146:147], s[6:7], 0, v[0:1]
	v_lshlrev_b64 v[18:19], 16, v[18:19]
	v_lshlrev_b64 v[20:21], 16, v[20:21]
	v_lshlrev_b64 v[22:23], 16, v[22:23]
	v_lshlrev_b64 v[24:25], 16, v[24:25]
	v_lshlrev_b64 v[26:27], 16, v[26:27]
	v_lshlrev_b64 v[28:29], 16, v[28:29]
	v_lshlrev_b64 v[30:31], 16, v[30:31]
	v_lshlrev_b64 v[32:33], 16, v[32:33]
	v_lshlrev_b64 v[34:35], 16, v[34:35]
	v_lshlrev_b64 v[36:37], 16, v[36:37]
	v_lshlrev_b64 v[38:39], 16, v[38:39]
	v_lshlrev_b64 v[40:41], 16, v[40:41]
	v_lshlrev_b32_e32 v0, 2, v10
	v_add_f32_e32 v129, v129, v11
	v_lshl_add_u64 v[10:11], v[78:79], 0, v[80:81]
	v_lshl_add_u64 v[80:81], v[78:79], 0, v[84:85]
	v_lshl_add_u64 v[84:85], v[78:79], 0, v[86:87]
	v_lshl_add_u64 v[86:87], v[78:79], 0, v[88:89]
	v_lshl_add_u64 v[88:89], v[78:79], 0, v[90:91]
	v_lshl_add_u64 v[90:91], v[78:79], 0, v[92:93]
	v_lshl_add_u64 v[152:153], v[146:147], 0, v[18:19]
	v_lshl_add_u64 v[154:155], v[146:147], 0, v[20:21]
	v_lshl_add_u64 v[156:157], v[146:147], 0, v[22:23]
	v_lshl_add_u64 v[158:159], v[146:147], 0, v[24:25]
	v_lshl_add_u64 v[160:161], v[146:147], 0, v[26:27]
	v_lshl_add_u64 v[162:163], v[146:147], 0, v[28:29]
	v_lshl_add_u64 v[164:165], v[146:147], 0, v[30:31]
	v_lshl_add_u64 v[166:167], v[146:147], 0, v[32:33]
	v_lshl_add_u64 v[168:169], v[146:147], 0, v[34:35]
	v_lshl_add_u64 v[170:171], v[146:147], 0, v[36:37]
	v_lshl_add_u64 v[172:173], v[146:147], 0, v[38:39]
	v_lshl_add_u64 v[174:175], v[146:147], 0, v[40:41]
	global_load_dwordx4 v[18:21], v[10:11], off nt
	global_load_dwordx4 v[22:25], v[80:81], off nt
	global_load_dwordx4 v[26:29], v[84:85], off nt
	global_load_dwordx4 v[30:33], v[86:87], off nt
	global_load_dwordx4 v[34:37], v[88:89], off nt
	global_load_dwordx4 v[38:41], v[90:91], off nt
	v_ashrrev_i32_e32 v43, 31, v42
	v_ashrrev_i32_e32 v45, 31, v44
	v_ashrrev_i32_e32 v47, 31, v46
	v_ashrrev_i32_e32 v49, 31, v48
	v_ashrrev_i32_e32 v51, 31, v50
	v_ashrrev_i32_e32 v53, 31, v52
	v_ashrrev_i32_e32 v55, 31, v54
	v_ashrrev_i32_e32 v57, 31, v56
	v_ashrrev_i32_e32 v59, 31, v58
	v_ashrrev_i32_e32 v61, 31, v60
	v_ashrrev_i32_e32 v63, 31, v62
	v_ashrrev_i32_e32 v65, 31, v64
	v_ashrrev_i32_e32 v67, 31, v66
	v_ashrrev_i32_e32 v69, 31, v68
	v_ashrrev_i32_e32 v71, 31, v70
	v_ashrrev_i32_e32 v73, 31, v72
	v_ashrrev_i32_e32 v75, 31, v74
	v_ashrrev_i32_e32 v77, 31, v76
	v_lshlrev_b64 v[108:109], 17, v[42:43]
	v_lshlrev_b64 v[110:111], 17, v[44:45]
	v_lshlrev_b64 v[112:113], 17, v[46:47]
	v_lshlrev_b64 v[114:115], 17, v[48:49]
	v_lshlrev_b64 v[116:117], 17, v[50:51]
	v_lshlrev_b64 v[118:119], 17, v[52:53]
	v_lshlrev_b64 v[120:121], 17, v[54:55]
	v_lshlrev_b64 v[122:123], 17, v[56:57]
	v_lshlrev_b64 v[124:125], 17, v[58:59]
	v_lshlrev_b64 v[126:127], 17, v[60:61]
	v_lshlrev_b64 v[130:131], 17, v[62:63]
	v_lshlrev_b64 v[132:133], 17, v[64:65]
	v_lshlrev_b64 v[134:135], 17, v[66:67]
	v_lshlrev_b64 v[136:137], 17, v[68:69]
	v_lshlrev_b64 v[138:139], 17, v[70:71]
	v_lshlrev_b64 v[140:141], 17, v[72:73]
	v_lshlrev_b64 v[142:143], 17, v[74:75]
	v_lshlrev_b64 v[144:145], 17, v[76:77]
	v_lshlrev_b64 v[42:43], 16, v[42:43]
	v_lshlrev_b64 v[44:45], 16, v[44:45]
	v_lshlrev_b64 v[46:47], 16, v[46:47]
	v_lshlrev_b64 v[48:49], 16, v[48:49]
	v_lshlrev_b64 v[50:51], 16, v[50:51]
	v_lshlrev_b64 v[52:53], 16, v[52:53]
	v_lshlrev_b64 v[54:55], 16, v[54:55]
	v_lshlrev_b64 v[56:57], 16, v[56:57]
	v_lshlrev_b64 v[58:59], 16, v[58:59]
	v_lshlrev_b64 v[60:61], 16, v[60:61]
	v_lshlrev_b64 v[62:63], 16, v[62:63]
	v_lshlrev_b64 v[64:65], 16, v[64:65]
	v_lshlrev_b64 v[66:67], 16, v[66:67]
	v_lshlrev_b64 v[68:69], 16, v[68:69]
	v_lshlrev_b64 v[70:71], 16, v[70:71]
	v_lshlrev_b64 v[72:73], 16, v[72:73]
	v_lshlrev_b64 v[74:75], 16, v[74:75]
	v_lshlrev_b64 v[76:77], 16, v[76:77]
	v_lshl_add_u64 v[92:93], v[78:79], 0, v[94:95]
	v_lshl_add_u64 v[94:95], v[78:79], 0, v[96:97]
	v_lshl_add_u64 v[96:97], v[78:79], 0, v[98:99]
	v_lshl_add_u64 v[98:99], v[78:79], 0, v[100:101]
	v_lshl_add_u64 v[100:101], v[78:79], 0, v[102:103]
	v_lshl_add_u64 v[102:103], v[78:79], 0, v[104:105]
	v_lshl_add_u64 v[104:105], v[78:79], 0, v[106:107]
	v_lshl_add_u64 v[106:107], v[78:79], 0, v[108:109]
	v_lshl_add_u64 v[108:109], v[78:79], 0, v[110:111]
	v_lshl_add_u64 v[110:111], v[78:79], 0, v[112:113]
	v_lshl_add_u64 v[112:113], v[78:79], 0, v[114:115]
	v_lshl_add_u64 v[114:115], v[78:79], 0, v[116:117]
	v_lshl_add_u64 v[116:117], v[78:79], 0, v[118:119]
	v_lshl_add_u64 v[118:119], v[78:79], 0, v[120:121]
	v_lshl_add_u64 v[120:121], v[78:79], 0, v[122:123]
	v_lshl_add_u64 v[122:123], v[78:79], 0, v[124:125]
	v_lshl_add_u64 v[124:125], v[78:79], 0, v[126:127]
	v_lshl_add_u64 v[126:127], v[78:79], 0, v[130:131]
	v_lshl_add_u64 v[130:131], v[78:79], 0, v[132:133]
	v_lshl_add_u64 v[132:133], v[78:79], 0, v[134:135]
	v_lshl_add_u64 v[134:135], v[78:79], 0, v[136:137]
	v_lshl_add_u64 v[136:137], v[78:79], 0, v[138:139]
	v_lshl_add_u64 v[138:139], v[78:79], 0, v[140:141]
	v_lshl_add_u64 v[140:141], v[78:79], 0, v[142:143]
	v_lshl_add_u64 v[142:143], v[78:79], 0, v[144:145]
	v_lshl_add_u64 v[150:151], v[146:147], 0, v[82:83]
	v_lshl_add_u64 v[148:149], v[146:147], 0, v[148:149]
	v_lshl_add_u64 v[176:177], v[146:147], 0, v[42:43]
	v_lshl_add_u64 v[178:179], v[146:147], 0, v[44:45]
	v_lshl_add_u64 v[180:181], v[146:147], 0, v[46:47]
	v_lshl_add_u64 v[182:183], v[146:147], 0, v[48:49]
	v_lshl_add_u64 v[184:185], v[146:147], 0, v[50:51]
	v_lshl_add_u64 v[186:187], v[146:147], 0, v[52:53]
	v_lshl_add_u64 v[188:189], v[146:147], 0, v[54:55]
	v_lshl_add_u64 v[190:191], v[146:147], 0, v[56:57]
	v_lshl_add_u64 v[192:193], v[146:147], 0, v[58:59]
	v_lshl_add_u64 v[194:195], v[146:147], 0, v[60:61]
	v_lshl_add_u64 v[196:197], v[146:147], 0, v[62:63]
	v_lshl_add_u64 v[198:199], v[146:147], 0, v[64:65]
	v_lshl_add_u64 v[200:201], v[146:147], 0, v[66:67]
	v_lshl_add_u64 v[202:203], v[146:147], 0, v[68:69]
	v_lshl_add_u64 v[204:205], v[146:147], 0, v[70:71]
	v_lshl_add_u64 v[206:207], v[146:147], 0, v[72:73]
	v_lshl_add_u64 v[208:209], v[146:147], 0, v[74:75]
	v_lshl_add_u64 v[146:147], v[146:147], 0, v[76:77]
	global_load_dwordx4 v[42:45], v[92:93], off nt
	global_load_dwordx4 v[46:49], v[94:95], off nt
	global_load_dwordx4 v[50:53], v[96:97], off nt
	global_load_dwordx4 v[54:57], v[98:99], off nt
	global_load_dwordx4 v[58:61], v[100:101], off nt
	global_load_dwordx4 v[62:65], v[102:103], off nt
	global_load_dwordx4 v[66:69], v[104:105], off nt
	global_load_dwordx4 v[70:73], v[106:107], off nt
	global_load_dwordx4 v[74:77], v[108:109], off nt
	global_load_dwordx4 v[78:81], v[110:111], off nt
	global_load_dwordx4 v[82:85], v[112:113], off nt
	global_load_dwordx4 v[86:89], v[114:115], off nt
	global_load_dwordx4 v[90:93], v[116:117], off nt
	global_load_dwordx4 v[94:97], v[118:119], off nt
	global_load_dwordx4 v[98:101], v[120:121], off nt
	global_load_dwordx4 v[102:105], v[122:123], off nt
	global_load_dwordx4 v[106:109], v[124:125], off nt
	global_load_dwordx4 v[110:113], v[126:127], off nt
	global_load_dwordx4 v[114:117], v[130:131], off nt
	s_nop 0
	global_load_dwordx4 v[118:121], v[132:133], off nt
	global_load_dwordx4 v[122:125], v[134:135], off nt
	s_nop 0
	global_load_dwordx4 v[130:133], v[136:137], off nt
	s_nop 0
	global_load_dwordx4 v[134:137], v[138:139], off nt
	s_nop 0
	global_load_dwordx4 v[138:141], v[140:141], off nt
	s_nop 0
	global_load_dwordx4 v[142:145], v[142:143], off nt
	v_ashrrev_i32_e32 v3, 31, v2
	v_lshlrev_b64 v[2:3], 17, v[2:3]
	v_lshl_add_u64 v[2:3], s[8:9], 0, v[2:3]
	v_lshl_add_u64 v[2:3], v[2:3], 0, v[0:1]
	v_lshlrev_b32_e32 v0, 10, v9
	v_exp_f32_e32 v9, v129
	v_cndmask_b32_e32 v210, 0, v7, vcc
	v_lshl_add_u64 v[2:3], v[2:3], 0, v[0:1]
	v_add_u32_e32 v5, s13, v5
	v_ldexp_f32 v0, v9, v210
	v_sub_f32_e32 v0, 1.0, v0
	v_cmp_gt_f32_e32 vcc, s15, v0
	global_store_dwordx2 v[150:151], v[12:13], off
	s_nop 0
	v_cndmask_b32_e64 v9, 0, 32, vcc
	v_ldexp_f32 v0, v0, v9
	v_log_f32_e32 v0, v0
	v_cndmask_b32_e32 v9, 0, v8, vcc
	v_sub_f32_e32 v0, v0, v9
	v_mul_f32_e32 v9, 0x43000000, v0
	v_cmp_gt_f32_e32 vcc, s14, v9
	s_nop 1
	v_cndmask_b32_e32 v9, 0, v6, vcc
	v_fmac_f32_e32 v9, 0x43000000, v0
	v_exp_f32_e32 v9, v9
	v_cndmask_b32_e32 v0, 0, v7, vcc
	v_ldexp_f32 v0, v9, v0
	s_waitcnt vmcnt(32)
	v_pk_fma_f32 v[10:11], v[0:1], 0, v[16:17] op_sel_hi:[0,0,1]
	v_pk_fma_f32 v[14:15], v[0:1], 0, v[14:15] op_sel_hi:[0,0,1]
	v_cvt_pk_bf16_f32 v16, v14, v15
	v_cvt_pk_bf16_f32 v17, v10, v11
	s_waitcnt vmcnt(31)
	v_pk_fma_f32 v[10:11], v[0:1], v[10:11], v[20:21] op_sel_hi:[0,1,1]
	v_pk_fma_f32 v[14:15], v[0:1], v[14:15], v[18:19] op_sel_hi:[0,1,1]
	global_store_dwordx2 v[148:149], v[16:17], off
	v_cvt_pk_bf16_f32 v16, v14, v15
	v_cvt_pk_bf16_f32 v17, v10, v11
	s_waitcnt vmcnt(31)
	v_pk_fma_f32 v[10:11], v[0:1], v[10:11], v[24:25] op_sel_hi:[0,1,1]
	v_pk_fma_f32 v[14:15], v[0:1], v[14:15], v[22:23] op_sel_hi:[0,1,1]
	global_store_dwordx2 v[152:153], v[16:17], off
	v_cvt_pk_bf16_f32 v16, v14, v15
	v_cvt_pk_bf16_f32 v17, v10, v11
	s_waitcnt vmcnt(31)
	v_pk_fma_f32 v[10:11], v[0:1], v[10:11], v[28:29] op_sel_hi:[0,1,1]
	v_pk_fma_f32 v[14:15], v[0:1], v[14:15], v[26:27] op_sel_hi:[0,1,1]
	global_store_dwordx2 v[154:155], v[16:17], off
	v_cvt_pk_bf16_f32 v16, v14, v15
	v_cvt_pk_bf16_f32 v17, v10, v11
	s_waitcnt vmcnt(31)
	v_pk_fma_f32 v[10:11], v[0:1], v[10:11], v[32:33] op_sel_hi:[0,1,1]
	v_pk_fma_f32 v[14:15], v[0:1], v[14:15], v[30:31] op_sel_hi:[0,1,1]
	global_store_dwordx2 v[156:157], v[16:17], off
	v_cvt_pk_bf16_f32 v16, v14, v15
	v_cvt_pk_bf16_f32 v17, v10, v11
	s_waitcnt vmcnt(31)
	v_pk_fma_f32 v[10:11], v[0:1], v[10:11], v[36:37] op_sel_hi:[0,1,1]
	v_pk_fma_f32 v[14:15], v[0:1], v[14:15], v[34:35] op_sel_hi:[0,1,1]
	global_store_dwordx2 v[158:159], v[16:17], off
	v_cvt_pk_bf16_f32 v16, v14, v15
	v_cvt_pk_bf16_f32 v17, v10, v11
	s_waitcnt vmcnt(31)
	v_pk_fma_f32 v[10:11], v[0:1], v[10:11], v[40:41] op_sel_hi:[0,1,1]
	v_pk_fma_f32 v[14:15], v[0:1], v[14:15], v[38:39] op_sel_hi:[0,1,1]
	global_store_dwordx2 v[160:161], v[16:17], off
	v_cvt_pk_bf16_f32 v16, v14, v15
	v_cvt_pk_bf16_f32 v17, v10, v11
	s_waitcnt vmcnt(31)
	v_pk_fma_f32 v[10:11], v[0:1], v[10:11], v[44:45] op_sel_hi:[0,1,1]
	v_pk_fma_f32 v[14:15], v[0:1], v[14:15], v[42:43] op_sel_hi:[0,1,1]
	global_store_dwordx2 v[162:163], v[16:17], off
	v_cvt_pk_bf16_f32 v16, v14, v15
	v_cvt_pk_bf16_f32 v17, v10, v11
	s_waitcnt vmcnt(31)
	v_pk_fma_f32 v[10:11], v[0:1], v[10:11], v[48:49] op_sel_hi:[0,1,1]
	v_pk_fma_f32 v[14:15], v[0:1], v[14:15], v[46:47] op_sel_hi:[0,1,1]
	global_store_dwordx2 v[164:165], v[16:17], off
	v_cvt_pk_bf16_f32 v16, v14, v15
	v_cvt_pk_bf16_f32 v17, v10, v11
	s_waitcnt vmcnt(31)
	v_pk_fma_f32 v[10:11], v[0:1], v[10:11], v[52:53] op_sel_hi:[0,1,1]
	v_pk_fma_f32 v[14:15], v[0:1], v[14:15], v[50:51] op_sel_hi:[0,1,1]
	global_store_dwordx2 v[166:167], v[16:17], off
	v_cvt_pk_bf16_f32 v16, v14, v15
	v_cvt_pk_bf16_f32 v17, v10, v11
	s_waitcnt vmcnt(31)
	v_pk_fma_f32 v[10:11], v[0:1], v[10:11], v[56:57] op_sel_hi:[0,1,1]
	v_pk_fma_f32 v[14:15], v[0:1], v[14:15], v[54:55] op_sel_hi:[0,1,1]
	global_store_dwordx2 v[168:169], v[16:17], off
	v_cvt_pk_bf16_f32 v16, v14, v15
	v_cvt_pk_bf16_f32 v17, v10, v11
	s_waitcnt vmcnt(31)
	v_pk_fma_f32 v[10:11], v[0:1], v[10:11], v[60:61] op_sel_hi:[0,1,1]
	v_pk_fma_f32 v[14:15], v[0:1], v[14:15], v[58:59] op_sel_hi:[0,1,1]
	global_store_dwordx2 v[170:171], v[16:17], off
	v_cvt_pk_bf16_f32 v16, v14, v15
	v_cvt_pk_bf16_f32 v17, v10, v11
	s_waitcnt vmcnt(31)
	v_pk_fma_f32 v[10:11], v[0:1], v[10:11], v[64:65] op_sel_hi:[0,1,1]
	v_pk_fma_f32 v[14:15], v[0:1], v[14:15], v[62:63] op_sel_hi:[0,1,1]
	global_store_dwordx2 v[172:173], v[16:17], off
	v_cvt_pk_bf16_f32 v16, v14, v15
	v_cvt_pk_bf16_f32 v17, v10, v11
	s_waitcnt vmcnt(31)
	v_pk_fma_f32 v[10:11], v[0:1], v[10:11], v[68:69] op_sel_hi:[0,1,1]
	v_pk_fma_f32 v[14:15], v[0:1], v[14:15], v[66:67] op_sel_hi:[0,1,1]
	global_store_dwordx2 v[174:175], v[16:17], off
	v_cvt_pk_bf16_f32 v16, v14, v15
	v_cvt_pk_bf16_f32 v17, v10, v11
	s_waitcnt vmcnt(31)
	v_pk_fma_f32 v[10:11], v[0:1], v[10:11], v[72:73] op_sel_hi:[0,1,1]
	v_pk_fma_f32 v[14:15], v[0:1], v[14:15], v[70:71] op_sel_hi:[0,1,1]
	global_store_dwordx2 v[176:177], v[16:17], off
	v_cvt_pk_bf16_f32 v16, v14, v15
	v_cvt_pk_bf16_f32 v17, v10, v11
	s_waitcnt vmcnt(31)
	v_pk_fma_f32 v[10:11], v[0:1], v[10:11], v[76:77] op_sel_hi:[0,1,1]
	v_pk_fma_f32 v[14:15], v[0:1], v[14:15], v[74:75] op_sel_hi:[0,1,1]
	global_store_dwordx2 v[178:179], v[16:17], off
	v_cvt_pk_bf16_f32 v16, v14, v15
	v_cvt_pk_bf16_f32 v17, v10, v11
	s_waitcnt vmcnt(31)
	v_pk_fma_f32 v[10:11], v[0:1], v[10:11], v[80:81] op_sel_hi:[0,1,1]
	v_pk_fma_f32 v[14:15], v[0:1], v[14:15], v[78:79] op_sel_hi:[0,1,1]
	global_store_dwordx2 v[180:181], v[16:17], off
	v_cvt_pk_bf16_f32 v16, v14, v15
	v_cvt_pk_bf16_f32 v17, v10, v11
	s_waitcnt vmcnt(31)
	v_pk_fma_f32 v[10:11], v[0:1], v[10:11], v[84:85] op_sel_hi:[0,1,1]
	v_pk_fma_f32 v[14:15], v[0:1], v[14:15], v[82:83] op_sel_hi:[0,1,1]
	global_store_dwordx2 v[182:183], v[16:17], off
	v_cvt_pk_bf16_f32 v16, v14, v15
	v_cvt_pk_bf16_f32 v17, v10, v11
	s_waitcnt vmcnt(31)
	v_pk_fma_f32 v[10:11], v[0:1], v[10:11], v[88:89] op_sel_hi:[0,1,1]
	v_pk_fma_f32 v[14:15], v[0:1], v[14:15], v[86:87] op_sel_hi:[0,1,1]
	global_store_dwordx2 v[184:185], v[16:17], off
	v_cvt_pk_bf16_f32 v16, v14, v15
	v_cvt_pk_bf16_f32 v17, v10, v11
	s_waitcnt vmcnt(31)
	v_pk_fma_f32 v[10:11], v[0:1], v[10:11], v[92:93] op_sel_hi:[0,1,1]
	v_pk_fma_f32 v[14:15], v[0:1], v[14:15], v[90:91] op_sel_hi:[0,1,1]
	global_store_dwordx2 v[186:187], v[16:17], off
	v_cvt_pk_bf16_f32 v16, v14, v15
	v_cvt_pk_bf16_f32 v17, v10, v11
	s_waitcnt vmcnt(31)
	v_pk_fma_f32 v[10:11], v[0:1], v[10:11], v[96:97] op_sel_hi:[0,1,1]
	v_pk_fma_f32 v[14:15], v[0:1], v[14:15], v[94:95] op_sel_hi:[0,1,1]
	global_store_dwordx2 v[188:189], v[16:17], off
	v_cvt_pk_bf16_f32 v16, v14, v15
	v_cvt_pk_bf16_f32 v17, v10, v11
	s_waitcnt vmcnt(31)
	v_pk_fma_f32 v[10:11], v[0:1], v[10:11], v[100:101] op_sel_hi:[0,1,1]
	v_pk_fma_f32 v[14:15], v[0:1], v[14:15], v[98:99] op_sel_hi:[0,1,1]
	global_store_dwordx2 v[190:191], v[16:17], off
	v_cvt_pk_bf16_f32 v16, v14, v15
	v_cvt_pk_bf16_f32 v17, v10, v11
	s_waitcnt vmcnt(31)
	v_pk_fma_f32 v[10:11], v[0:1], v[10:11], v[104:105] op_sel_hi:[0,1,1]
	v_pk_fma_f32 v[14:15], v[0:1], v[14:15], v[102:103] op_sel_hi:[0,1,1]
	global_store_dwordx2 v[192:193], v[16:17], off
	v_cvt_pk_bf16_f32 v16, v14, v15
	v_cvt_pk_bf16_f32 v17, v10, v11
	s_waitcnt vmcnt(31)
	v_pk_fma_f32 v[10:11], v[0:1], v[10:11], v[108:109] op_sel_hi:[0,1,1]
	v_pk_fma_f32 v[14:15], v[0:1], v[14:15], v[106:107] op_sel_hi:[0,1,1]
	global_store_dwordx2 v[194:195], v[16:17], off
	v_cvt_pk_bf16_f32 v16, v14, v15
	v_cvt_pk_bf16_f32 v17, v10, v11
	s_waitcnt vmcnt(31)
	v_pk_fma_f32 v[10:11], v[0:1], v[10:11], v[112:113] op_sel_hi:[0,1,1]
	v_pk_fma_f32 v[14:15], v[0:1], v[14:15], v[110:111] op_sel_hi:[0,1,1]
	global_store_dwordx2 v[196:197], v[16:17], off
	v_cvt_pk_bf16_f32 v16, v14, v15
	v_cvt_pk_bf16_f32 v17, v10, v11
	s_waitcnt vmcnt(31)
	v_pk_fma_f32 v[10:11], v[0:1], v[10:11], v[116:117] op_sel_hi:[0,1,1]
	v_pk_fma_f32 v[14:15], v[0:1], v[14:15], v[114:115] op_sel_hi:[0,1,1]
	global_store_dwordx2 v[198:199], v[16:17], off
	v_cvt_pk_bf16_f32 v16, v14, v15
	v_cvt_pk_bf16_f32 v17, v10, v11
	s_waitcnt vmcnt(31)
	v_pk_fma_f32 v[10:11], v[0:1], v[10:11], v[120:121] op_sel_hi:[0,1,1]
	v_pk_fma_f32 v[14:15], v[0:1], v[14:15], v[118:119] op_sel_hi:[0,1,1]
	global_store_dwordx2 v[200:201], v[16:17], off
	v_cvt_pk_bf16_f32 v16, v14, v15
	v_cvt_pk_bf16_f32 v17, v10, v11
	s_waitcnt vmcnt(31)
	v_pk_fma_f32 v[10:11], v[0:1], v[10:11], v[124:125] op_sel_hi:[0,1,1]
	v_pk_fma_f32 v[14:15], v[0:1], v[14:15], v[122:123] op_sel_hi:[0,1,1]
	global_store_dwordx2 v[202:203], v[16:17], off
	v_cvt_pk_bf16_f32 v16, v14, v15
	v_cvt_pk_bf16_f32 v17, v10, v11
	s_waitcnt vmcnt(31)
	v_pk_fma_f32 v[10:11], v[0:1], v[10:11], v[132:133] op_sel_hi:[0,1,1]
	v_pk_fma_f32 v[14:15], v[0:1], v[14:15], v[130:131] op_sel_hi:[0,1,1]
	global_store_dwordx2 v[204:205], v[16:17], off
	v_cvt_pk_bf16_f32 v16, v14, v15
	v_cvt_pk_bf16_f32 v17, v10, v11
	s_waitcnt vmcnt(31)
	v_pk_fma_f32 v[10:11], v[0:1], v[10:11], v[136:137] op_sel_hi:[0,1,1]
	v_pk_fma_f32 v[14:15], v[0:1], v[14:15], v[134:135] op_sel_hi:[0,1,1]
	global_store_dwordx2 v[206:207], v[16:17], off
	v_cvt_pk_bf16_f32 v16, v14, v15
	v_cvt_pk_bf16_f32 v17, v10, v11
	s_waitcnt vmcnt(31)
	v_pk_fma_f32 v[10:11], v[0:1], v[10:11], v[140:141] op_sel_hi:[0,1,1]
	v_pk_fma_f32 v[14:15], v[0:1], v[14:15], v[138:139] op_sel_hi:[0,1,1]
	global_store_dwordx2 v[208:209], v[16:17], off
	v_cvt_pk_bf16_f32 v16, v14, v15
	v_cvt_pk_bf16_f32 v17, v10, v11
	s_waitcnt vmcnt(31)
	v_pk_fma_f32 v[10:11], v[0:1], v[10:11], v[144:145] op_sel_hi:[0,1,1]
	v_pk_fma_f32 v[14:15], v[0:1], v[14:15], v[142:143] op_sel_hi:[0,1,1]
	global_store_dwordx2 v[146:147], v[16:17], off
	global_store_dword v[2:3], v14, off
	global_store_dword v[2:3], v15, off offset:1024
	global_store_dword v[2:3], v10, off offset:2048
	global_store_dword v[2:3], v11, off offset:3072
	s_andn2_b64 exec, exec, s[10:11]
	s_cbranch_execnz .LBB0_1155
